# G5 K-loop: next K-step LDS fragment reads placed one per MFMA gap (register double buffer), instead of read-then-wait-then-MFMA
# speedup vs baseline: 1.0066x; 1.0066x over previous
.LBB0_245:
	s_or_b64 exec, exec, s[6:7]
	s_add_i32 s6, s13, 0
	v_add_u32_e32 v131, s6, v182
	v_add_u32_e32 v130, s6, v183
	v_add_u32_e32 v133, v131, v184
	v_add_u32_e32 v230, v130, v184
	ds_read_b128 v[190:193], v133
	ds_read_b128 v[194:197], v133 offset:4096
	ds_read_b128 v[198:201], v133 offset:8192
	ds_read_b128 v[202:205], v133 offset:12288
	ds_read_b128 v[206:209], v230 offset:32768
	ds_read_b128 v[210:213], v230 offset:36864
	v_add_u32_e32 v133, v131, v181
	v_add_u32_e32 v230, v130, v181
	s_setprio 1
	s_waitcnt lgkmcnt(0)
	v_mfma_f32_32x32x16_bf16 v[112:127], v[190:193], v[206:209], v[112:127]
	ds_read_b128 v[214:217], v133
	v_mfma_f32_32x32x16_bf16 v[96:111], v[190:193], v[210:213], v[96:111]
	ds_read_b128 v[218:221], v133 offset:4096
	v_mfma_f32_32x32x16_bf16 v[80:95], v[194:197], v[206:209], v[80:95]
	ds_read_b128 v[234:237], v133 offset:8192
	v_mfma_f32_32x32x16_bf16 v[64:79], v[194:197], v[210:213], v[64:79]
	ds_read_b128 v[238:241], v133 offset:12288
	v_mfma_f32_32x32x16_bf16 v[48:63], v[198:201], v[206:209], v[48:63]
	ds_read_b128 v[242:245], v230 offset:32768
	v_mfma_f32_32x32x16_bf16 v[32:47], v[198:201], v[210:213], v[32:47]
	ds_read_b128 v[246:249], v230 offset:36864
	v_mfma_f32_32x32x16_bf16 v[16:31], v[202:205], v[206:209], v[16:31]
	v_mfma_f32_32x32x16_bf16 v[0:15], v[202:205], v[210:213], v[0:15]
	s_setprio 0
	v_add_u32_e32 v133, v131, v172
	v_add_u32_e32 v230, v130, v172
	s_setprio 1
	s_waitcnt lgkmcnt(0)
	v_mfma_f32_32x32x16_bf16 v[112:127], v[214:217], v[242:245], v[112:127]
	ds_read_b128 v[190:193], v133
	v_mfma_f32_32x32x16_bf16 v[96:111], v[214:217], v[246:249], v[96:111]
	ds_read_b128 v[194:197], v133 offset:4096
	v_mfma_f32_32x32x16_bf16 v[80:95], v[218:221], v[242:245], v[80:95]
	ds_read_b128 v[198:201], v133 offset:8192
	v_mfma_f32_32x32x16_bf16 v[64:79], v[218:221], v[246:249], v[64:79]
	ds_read_b128 v[202:205], v133 offset:12288
	v_mfma_f32_32x32x16_bf16 v[48:63], v[234:237], v[242:245], v[48:63]
	ds_read_b128 v[206:209], v230 offset:32768
	v_mfma_f32_32x32x16_bf16 v[32:47], v[234:237], v[246:249], v[32:47]
	ds_read_b128 v[210:213], v230 offset:36864
	v_mfma_f32_32x32x16_bf16 v[16:31], v[238:241], v[242:245], v[16:31]
	v_mfma_f32_32x32x16_bf16 v[0:15], v[238:241], v[246:249], v[0:15]
	s_setprio 0
	s_and_saveexec_b64 s[6:7], s[0:1]
	s_cbranch_execz .LBB0_247
	s_xor_b32 s13, s13, 0x10000
	s_add_i32 s13, s13, 0
	v_add_u32_e32 v133, s13, v180
	v_add_u32_e32 v227, s13, v179
	v_readfirstlane_b32 s14, v133
	v_lshl_add_u64 v[228:229], v[150:151], 0, s[4:5]
	s_mov_b32 m0, s14
	v_readfirstlane_b32 s14, v227
	v_add_u32_e32 v222, s13, v178
	global_load_lds_dwordx4 v[228:229], off
	v_lshl_add_u64 v[228:229], v[152:153], 0, s[4:5]
	s_mov_b32 m0, s14
	v_readfirstlane_b32 s14, v222
	v_add_u32_e32 v223, s13, v177
	global_load_lds_dwordx4 v[228:229], off
	v_lshl_add_u64 v[228:229], v[154:155], 0, s[4:5]
	s_mov_b32 m0, s14
	v_readfirstlane_b32 s13, v223
	v_add_u32_e32 v133, 0x8000, v133
	global_load_lds_dwordx4 v[228:229], off
	v_lshl_add_u64 v[228:229], v[156:157], 0, s[4:5]
	s_mov_b32 m0, s13
	v_readfirstlane_b32 s13, v133
	v_add_u32_e32 v133, 0x8000, v227
	global_load_lds_dwordx4 v[228:229], off
	v_lshl_add_u64 v[228:229], v[158:159], 0, s[4:5]
	s_mov_b32 m0, s13
	v_readfirstlane_b32 s13, v133
	v_add_u32_e32 v133, 0x8000, v222
	global_load_lds_dwordx4 v[228:229], off
	v_lshl_add_u64 v[228:229], v[160:161], 0, s[4:5]
	s_mov_b32 m0, s13
	v_readfirstlane_b32 s13, v133
	v_add_u32_e32 v133, 0x8000, v223
	global_load_lds_dwordx4 v[228:229], off
	v_lshl_add_u64 v[228:229], v[162:163], 0, s[4:5]
	s_mov_b32 m0, s13
	v_readfirstlane_b32 s13, v133
	global_load_lds_dwordx4 v[228:229], off
	v_lshl_add_u64 v[228:229], v[164:165], 0, s[4:5]
	s_mov_b32 m0, s13
	s_nop 0
	global_load_lds_dwordx4 v[228:229], off
.LBB0_247:
	s_or_b64 exec, exec, s[6:7]
	v_add_u32_e32 v133, v131, v171
	v_add_u32_e32 v230, v130, v171
	s_setprio 1
	s_waitcnt lgkmcnt(0)
	v_mfma_f32_32x32x16_bf16 v[112:127], v[190:193], v[206:209], v[112:127]
	ds_read_b128 v[214:217], v133
	v_mfma_f32_32x32x16_bf16 v[96:111], v[190:193], v[210:213], v[96:111]
	ds_read_b128 v[218:221], v133 offset:4096
	v_mfma_f32_32x32x16_bf16 v[80:95], v[194:197], v[206:209], v[80:95]
	ds_read_b128 v[234:237], v133 offset:8192
	v_mfma_f32_32x32x16_bf16 v[64:79], v[194:197], v[210:213], v[64:79]
	ds_read_b128 v[238:241], v133 offset:12288
	v_mfma_f32_32x32x16_bf16 v[48:63], v[198:201], v[206:209], v[48:63]
	ds_read_b128 v[242:245], v230 offset:32768
	v_mfma_f32_32x32x16_bf16 v[32:47], v[198:201], v[210:213], v[32:47]
	ds_read_b128 v[246:249], v230 offset:36864
	v_mfma_f32_32x32x16_bf16 v[16:31], v[202:205], v[206:209], v[16:31]
	v_mfma_f32_32x32x16_bf16 v[0:15], v[202:205], v[210:213], v[0:15]
	s_setprio 0
	s_setprio 1
	s_waitcnt lgkmcnt(0)
	v_mfma_f32_32x32x16_bf16 v[112:127], v[214:217], v[242:245], v[112:127]
	v_mfma_f32_32x32x16_bf16 v[96:111], v[214:217], v[246:249], v[96:111]
	v_mfma_f32_32x32x16_bf16 v[80:95], v[218:221], v[242:245], v[80:95]
	v_mfma_f32_32x32x16_bf16 v[64:79], v[218:221], v[246:249], v[64:79]
	v_mfma_f32_32x32x16_bf16 v[48:63], v[234:237], v[242:245], v[48:63]
	v_mfma_f32_32x32x16_bf16 v[32:47], v[234:237], v[246:249], v[32:47]
	v_mfma_f32_32x32x16_bf16 v[16:31], v[238:241], v[242:245], v[16:31]
	v_mfma_f32_32x32x16_bf16 v[0:15], v[238:241], v[246:249], v[0:15]
	s_setprio 0
	s_xor_b32 s6, s9, 1
	s_waitcnt vmcnt(0)
	s_add_u32 s4, s4, 0x80
	s_addc_u32 s5, s5, 0
	s_cmpk_lg_i32 s4, 0x780
	s_waitcnt vmcnt(0)
	s_barrier
	s_cbranch_scc1 .LBB0_243
	v_add_u32_e32 v139, s8, v128
	s_movk_i32 s0, 0x5f
	v_cmp_lt_i32_e64 s[0:1], s0, v139
	s_mov_b32 s4, 0x2aaaaaab
	s_nop 0
	v_cndmask_b32_e64 v128, v139, v128, s[0:1]
	v_mul_hi_i32 v130, v128, s4
	v_lshrrev_b32_e32 v131, 31, v130
	v_add_u32_e32 v130, v130, v131
	v_mul_lo_u32 v131, v130, 6
	v_sub_u32_e32 v128, v128, v131
	v_add_lshl_u32 v138, v128, v166, 8
	v_lshlrev_b32_e32 v128, 4, v132
	v_and_b32_e32 v128, 0x70, v128
	s_xor_b64 s[4:5], vcc, -1
	v_lshl_add_u64 v[136:137], s[38:39], 0, v[128:129]
	v_lshl_add_u64 v[134:135], s[40:41], 0, v[128:129]
	v_lshlrev_b32_e32 v140, 8, v130
	s_nor_b64 s[4:5], s[4:5], s[0:1]
	s_and_saveexec_b64 s[14:15], s[4:5]
	s_xor_b64 s[4:5], exec, s[14:15]
	s_cbranch_execz .LBB0_250
	s_lshl_b32 s7, s6, 16
	s_xor_b32 s13, s7, 0x10000
	v_add_u32_e32 v130, v138, v188
	s_add_i32 s13, s13, 0
	v_ashrrev_i32_e32 v131, 31, v130
	v_add_u32_e32 v132, v187, v138
	v_add_u32_e32 v128, s13, v180
	v_lshlrev_b64 v[130:131], 11, v[130:131]
	v_ashrrev_i32_e32 v133, 31, v132
	v_readfirstlane_b32 s14, v128
	v_add_u32_e32 v141, s13, v179
	v_lshlrev_b64 v[132:133], 11, v[132:133]
	v_lshl_add_u64 v[130:131], v[136:137], 0, v[130:131]
	s_mov_b32 m0, s14
	v_readfirstlane_b32 s14, v141
	v_add_u32_e32 v142, v186, v138
	v_lshl_add_u64 v[132:133], v[136:137], 0, v[132:133]
	global_load_lds_dwordx4 v[130:131], off
	s_mov_b32 m0, s14
	v_ashrrev_i32_e32 v143, 31, v142
	v_add_u32_e32 v144, v185, v138
	global_load_lds_dwordx4 v[132:133], off
	v_add_u32_e32 v132, s13, v178
	v_lshlrev_b64 v[142:143], 11, v[142:143]
	v_ashrrev_i32_e32 v145, 31, v144
	v_readfirstlane_b32 s14, v132
	v_add_u32_e32 v133, s13, v177
	v_add_u32_e32 v130, v140, v188
	v_lshlrev_b64 v[144:145], 11, v[144:145]
	v_lshl_add_u64 v[142:143], v[136:137], 0, v[142:143]
	s_mov_b32 m0, s14
	v_readfirstlane_b32 s13, v133
	v_ashrrev_i32_e32 v131, 31, v130
	v_add_u32_e32 v128, 0x8000, v128
	v_lshl_add_u64 v[144:145], v[136:137], 0, v[144:145]
	global_load_lds_dwordx4 v[142:143], off
	s_mov_b32 m0, s13
	v_lshlrev_b64 v[130:131], 11, v[130:131]
	v_readfirstlane_b32 s13, v128
	global_load_lds_dwordx4 v[144:145], off
	v_lshl_add_u64 v[130:131], v[134:135], 0, v[130:131]
	s_mov_b32 m0, s13
	v_add_u32_e32 v128, 0x8000, v141
	global_load_lds_dwordx4 v[130:131], off
	v_add_u32_e32 v130, v187, v140
	v_ashrrev_i32_e32 v131, 31, v130
	v_lshlrev_b64 v[130:131], 11, v[130:131]
	v_readfirstlane_b32 s13, v128
	v_lshl_add_u64 v[130:131], v[134:135], 0, v[130:131]
	s_mov_b32 m0, s13
	v_add_u32_e32 v128, 0x8000, v132
	global_load_lds_dwordx4 v[130:131], off
	v_add_u32_e32 v130, v186, v140
	v_ashrrev_i32_e32 v131, 31, v130
	v_lshlrev_b64 v[130:131], 11, v[130:131]
	v_readfirstlane_b32 s13, v128
	v_lshl_add_u64 v[130:131], v[134:135], 0, v[130:131]
	s_mov_b32 m0, s13
	v_add_u32_e32 v128, 0x8000, v133
	global_load_lds_dwordx4 v[130:131], off
	v_add_u32_e32 v130, v185, v140
	v_ashrrev_i32_e32 v131, 31, v130
	v_lshlrev_b64 v[130:131], 11, v[130:131]
	v_readfirstlane_b32 s13, v128
	v_lshl_add_u64 v[130:131], v[134:135], 0, v[130:131]
	s_mov_b32 m0, s13
	s_nop 0
	global_load_lds_dwordx4 v[130:131], off
